# gdn_seq chunk loop: coalesced LDS-DMA (global_load_lds_dwordx4) operand fetch into per-wave swizzled LDS staging + fragment ds_reads, hand-scheduled; LDS 76800
# speedup vs baseline: 1.1143x; 1.0357x over previous
.LBB0_552:
	v_add_u32_e32 v1, 0x100, v1
	s_movk_i32 s8, 0xfff
	v_cmp_lt_u32_e32 vcc, s8, v1
	ds_write_b16 v0, v113
	s_or_b64 s[0:1], vcc, s[0:1]
	v_add_u32_e32 v0, 0x200, v0
	s_andn2_b64 exec, exec, s[0:1]
	s_cbranch_execnz .LBB0_552
	s_or_b64 exec, exec, s[0:1]
	s_ashr_i32 s22, s24, 4
	s_bfe_u32 s25, s24, 0x20002
	s_lshl_b32 s0, s22, 2
	s_or_b32 s0, s0, s25
	s_lshl_b32 s18, s0, 5
	s_ashr_i32 s19, s18, 31
	s_mul_i32 s1, s0, 0x240000
	s_mul_hi_i32 s8, s18, 0x12000
	s_add_u32 s16, s30, s1
	s_addc_u32 s17, s31, s8
	v_mov_b32_e32 v143, v113
	v_lshl_add_u64 v[0:1], v[116:117], 1, s[16:17]
	s_lshl_b32 s1, s24, 5
	v_lshl_add_u64 v[0:1], v[0:1], 0, v[142:143]
	s_and_b32 s8, s1, 0x60
	v_add_co_u32_e32 v6, vcc, s26, v0
	s_waitcnt vmcnt(18)
	v_or_b32_e32 v22, s8, v98
	s_mov_b64 s[46:47], 0x4000
	v_addc_co_u32_e32 v7, vcc, 0, v1, vcc
	v_add_u32_e32 v112, v22, v173
	v_readlane_b32 s68, v251, 8
	v_lshl_add_u64 v[2:3], v[0:1], 0, s[46:47]
	v_lshl_add_u64 v[4:5], v[0:1], 0, s[10:11]
	v_add_co_u32_e32 v0, vcc, s42, v0
	v_or_b32_e32 v8, v22, v173
	v_lshlrev_b64 v[80:81], 1, v[112:113]
	v_readlane_b32 s72, v251, 12
	v_readlane_b32 s73, v251, 13
	v_addc_co_u32_e32 v1, vcc, 0, v1, vcc
	v_lshlrev_b32_e32 v36, 1, v8
	v_lshl_add_u64 v[8:9], s[16:17], 0, v[80:81]
	v_add_u32_e32 v56, v22, v174
	v_mov_b32_e32 v57, v113
	v_add_u32_e32 v58, v22, v175
	v_mov_b32_e32 v59, v113
	v_add_u32_e32 v112, v22, v176
	v_readlane_b32 s74, v251, 14
	v_readlane_b32 s75, v251, 15
	v_readlane_b32 s76, v251, 16
	v_readlane_b32 s77, v251, 17
	v_readlane_b32 s78, v251, 18
	v_readlane_b32 s79, v251, 19
	s_mov_b64 s[48:49], s[72:73]
	global_load_dwordx4 v[32:35], v[6:7], off
	global_load_dwordx4 v[44:47], v[0:1], off
	global_load_dwordx4 v[12:15], v[2:3], off offset:64
	global_load_dwordx4 v[16:19], v[2:3], off offset:128
	global_load_dwordx4 v[28:31], v[4:5], off offset:64
	s_nop 0
	global_load_dwordx4 v[0:3], v[2:3], off offset:192
	s_nop 0
	global_load_dwordx4 v[24:27], v[4:5], off offset:128
	s_nop 0
	global_load_dwordx4 v[4:7], v[4:5], off offset:192
	v_lshl_add_u64 v[10:11], v[56:57], 1, s[16:17]
	v_lshl_add_u64 v[20:21], v[58:59], 1, s[16:17]
	v_lshl_add_u64 v[22:23], v[112:113], 1, s[16:17]
	global_load_ushort v186, v36, s[16:17]
	global_load_ushort v188, v[8:9], off offset:256
	global_load_ushort v185, v[8:9], off offset:512
	global_load_ushort v89, v[8:9], off offset:768
	global_load_ushort v187, v[10:11], off offset:32
	global_load_ushort v189, v[20:21], off offset:32
	global_load_ushort v190, v[22:23], off offset:32
	global_load_ushort v91, v[8:9], off offset:32
	s_lshl_b64 s[18:19], s[18:19], 2
	s_mov_b64 s[52:53], s[76:77]
	v_lshl_add_u64 v[8:9], v[118:119], 1, s[16:17]
	s_add_u32 s46, s52, s18
	v_lshl_add_u64 v[8:9], v[8:9], 0, v[142:143]
	s_addc_u32 s47, s53, s19
	v_lshl_add_u64 v[10:11], v[8:9], 0, s[14:15]
	v_lshl_add_u64 v[20:21], s[16:17], 0, v[142:143]
	v_add_co_u32_e32 v8, vcc, s43, v8
	global_load_dword v88, v113, s[46:47]
	s_nop 0
	v_addc_co_u32_e32 v9, vcc, 0, v9, vcc
	v_lshl_add_u64 v[20:21], v[120:121], 1, v[20:21]
	s_mov_b64 s[46:47], 0xc000
	s_mov_b32 s1, 0xc000
	v_lshl_add_u64 v[22:23], v[20:21], 0, s[46:47]
	v_add_co_u32_e32 v20, vcc, s1, v20
	s_ashr_i32 s23, s22, 31
	s_nop 0
	v_addc_co_u32_e32 v21, vcc, 0, v21, vcc
	global_load_dwordx4 v[52:55], v[8:9], off
	global_load_dwordx4 v[48:51], v[10:11], off offset:64
	s_nop 0
	global_load_dwordx4 v[8:11], v[22:23], off offset:2048
	global_load_dwordx4 v[36:39], v[22:23], off offset:64
	global_load_dwordx4 v[40:43], v[20:21], off
	s_nop 0
	global_load_dwordx4 v[20:23], v[22:23], off offset:2112
	s_add_u32 s18, s3, s18
	s_addc_u32 s19, s4, s19
	s_lshl_b64 s[22:23], s[22:23], 22
	s_lshl_b32 s25, s25, 9
	s_and_b32 s24, s24, 3
	s_or_b32 s22, s22, s25
	s_lshl_b32 s24, s24, 7
	v_lshlrev_b32_e32 v84, 1, v56
	s_or_b32 s22, s22, s24
	v_mov_b32_e32 v56, 0
	s_mov_b32 s1, 0
	v_lshlrev_b32_e32 v112, 1, v112
	v_lshlrev_b32_e32 v82, 1, v58
	v_mov_b32_e32 v83, v113
	v_mov_b32_e32 v85, v113
	v_lshl_add_u64 v[86:87], v[140:141], 0, s[22:23]
	v_mov_b32_e32 v57, v56
	v_mov_b32_e32 v58, v56
	v_mov_b32_e32 v59, v56
	v_mov_b32_e32 v64, v56
	v_mov_b32_e32 v65, v56
	v_mov_b32_e32 v66, v56
	v_mov_b32_e32 v67, v56
	v_mov_b32_e32 v68, v56
	v_mov_b32_e32 v69, v56
	v_mov_b32_e32 v70, v56
	v_mov_b32_e32 v71, v56
	v_mov_b32_e32 v60, v56
	v_mov_b32_e32 v61, v56
	v_mov_b32_e32 v62, v56
	v_mov_b32_e32 v63, v56
	v_readlane_b32 s69, v251, 9
	v_readlane_b32 s70, v251, 10
	v_readlane_b32 s71, v251, 11
	v_readlane_b32 s80, v251, 20
	v_readlane_b32 s81, v251, 21
	v_readlane_b32 s82, v251, 22
	v_readlane_b32 s83, v251, 23
	s_mov_b64 s[50:51], s[74:75]
	s_mov_b64 s[54:55], s[78:79]
	s_waitcnt lgkmcnt(0)
	s_barrier
	v_and_b32_e32 v242, 63, v162
	v_lshrrev_b32_e32 v243, 6, v162
	v_and_b32_e32 v244, 15, v242
	v_lshrrev_b32_e32 v245, 4, v242
	v_readfirstlane_b32 s56, v243
	v_xor_b32_e32 v250, v244, v245
	v_lshlrev_b32_e32 v253, 12, v243
	v_lshl_add_u32 v253, v245, 8, v253
	v_add_u32_e32 v253, 0x4000, v253
	v_xor_b32_e32 v254, 0, v250
	v_lshl_add_u32 v204, v254, 4, v253
	v_xor_b32_e32 v254, 4, v250
	v_lshl_add_u32 v205, v254, 4, v253
	v_add_u32_e32 v205, 0x400, v205
	v_xor_b32_e32 v254, 8, v250
	v_lshl_add_u32 v206, v254, 4, v253
	v_add_u32_e32 v206, 0x800, v206
	v_xor_b32_e32 v254, 12, v250
	v_lshl_add_u32 v207, v254, 4, v253
	v_add_u32_e32 v207, 0xc00, v207
	v_lshrrev_b32_e32 v253, 3, v242
	v_and_b32_e32 v254, 7, v242
	v_xor_b32_e32 v254, v254, v253
	v_lshlrev_b32_e32 v254, 4, v254
	v_lshl_add_u32 v254, v253, 7, v254
	v_lshl_add_u32 v210, v243, 12, v254
	v_add_u32_e32 v210, 0xc000, v210
	v_lshl_add_u32 v211, v243, 11, v254
	v_add_u32_e32 v211, 0x10000, v211
	v_lshl_add_u32 v253, v243, 2, v245
	v_lshlrev_b32_e32 v212, 10, v253
	v_add_u32_e32 v254, s8, v244
	v_lshl_add_u32 v212, v254, 1, v212
	v_lshlrev_b32_e32 v253, 12, v243
	v_lshl_add_u32 v253, v244, 8, v253
	v_add_u32_e32 v253, 0x3400, v253
	v_xor_b32_e32 v254, 0, v250
	v_lshl_add_u32 v213, v254, 4, v253
	v_xor_b32_e32 v254, 4, v250
	v_lshl_add_u32 v214, v254, 4, v253
	v_xor_b32_e32 v254, 8, v250
	v_lshl_add_u32 v215, v254, 4, v253
	v_xor_b32_e32 v254, 12, v250
	v_lshl_add_u32 v216, v254, 4, v253
	v_and_b32_e32 v254, 7, v244
	v_xor_b32_e32 v250, v254, v245
	v_lshlrev_b32_e32 v253, 7, v244
	v_lshl_add_u32 v242, v243, 12, v253
	v_add_u32_e32 v242, 0xb400, v242
	v_lshl_add_u32 v253, v243, 11, v253
	v_add_u32_e32 v253, 0x10820, v253
	v_xor_b32_e32 v254, 0, v250
	v_lshl_add_u32 v217, v254, 4, v242
	v_lshl_add_u32 v221, v254, 4, v253
	v_xor_b32_e32 v254, 4, v250
	v_lshl_add_u32 v220, v254, 4, v242
	v_lshl_add_u32 v222, v254, 4, v253
	v_mul_u32_u24_e32 v253, 0x110, v244
	v_lshl_add_u32 v246, v245, 4, v253
	v_lshl_add_u32 v249, v245, 3, v253
	v_lshl_add_u32 v249, v243, 6, v249
	v_mul_u32_u24_e32 v253, 0x90, v244
	v_add_u32_e32 v253, 0x2200, v253
	v_lshl_add_u32 v248, v245, 4, v253
	v_lshl_add_u32 v247, v245, 3, v253
	v_lshl_add_u32 v247, v243, 5, v247
	s_add_u32 s20, s16, 0x12000
	s_addc_u32 s21, s17, 0
	s_add_u32 s22, s20, 0x4000
	s_addc_u32 s23, s21, 0
	s_mov_b64 s[46:47], s[18:19]
	s_mov_b64 s[50:51], 0x20000
	s_lshl_b32 s52, s56, 12
	s_add_u32 s53, s52, 0x7400
	s_add_u32 s54, s52, 0xb400
	s_add_u32 s52, s52, 0x3400
	s_lshl_b32 s55, s56, 11
	s_add_u32 s55, s55, 0x10820
	s_waitcnt vmcnt(15)
	ds_read_b128 v[148:151], v246 offset:0
	ds_read_b128 v[192:195], v246 offset:4352
	ds_read_b128 v[196:199], v246 offset:64
	ds_read_b128 v[200:203], v246 offset:4416
	s_waitcnt lgkmcnt(3)
	s_add_u32 m0, s52, 0x0
	v_mfma_f32_16x16x32_bf16 v[92:95], v[32:35], v[148:151], 0
	global_load_lds_dwordx4 v204, s[20:21]
	v_mfma_f32_16x16x32_bf16 v[72:75], v[148:151], v[44:47], 0
	s_waitcnt lgkmcnt(2)
	s_add_u32 m0, s52, 0x400
	v_mfma_f32_16x16x32_bf16 v[144:147], v[32:35], v[192:195], 0
	global_load_lds_dwordx4 v205, s[20:21]
	v_mfma_f32_16x16x32_bf16 v[76:79], v[192:195], v[44:47], 0
	ds_read_b128 v[148:151], v246 offset:128
	ds_read_b128 v[192:195], v246 offset:4480
	s_waitcnt lgkmcnt(3)
	s_add_u32 m0, s52, 0x800
	v_mfma_f32_16x16x32_bf16 v[92:95], v[12:15], v[196:199], v[92:95]
	global_load_lds_dwordx4 v206, s[20:21]
	v_mfma_f32_16x16x32_bf16 v[72:75], v[196:199], v[28:31], v[72:75]
	s_waitcnt lgkmcnt(2)
	s_add_u32 m0, s52, 0xc00
	v_mfma_f32_16x16x32_bf16 v[144:147], v[12:15], v[200:203], v[144:147]
	global_load_lds_dwordx4 v207, s[20:21]
	v_mfma_f32_16x16x32_bf16 v[76:79], v[200:203], v[28:31], v[76:79]
	ds_read_b128 v[196:199], v246 offset:192
	ds_read_b128 v[200:203], v246 offset:4544
	s_waitcnt lgkmcnt(3)
	s_add_u32 m0, s53, 0x0
	v_mfma_f32_16x16x32_bf16 v[92:95], v[16:19], v[148:151], v[92:95]
	global_load_lds_dwordx4 v204, s[22:23]
	v_mfma_f32_16x16x32_bf16 v[72:75], v[148:151], v[24:27], v[72:75]
	s_waitcnt lgkmcnt(2)
	s_add_u32 m0, s53, 0x400
	v_mfma_f32_16x16x32_bf16 v[144:147], v[16:19], v[192:195], v[144:147]
	global_load_lds_dwordx4 v205, s[22:23]
	v_mfma_f32_16x16x32_bf16 v[76:79], v[192:195], v[24:27], v[76:79]
	s_waitcnt lgkmcnt(1)
	s_add_u32 m0, s53, 0x800
	v_mfma_f32_16x16x32_bf16 v[92:95], v[0:3], v[196:199], v[92:95]
	global_load_lds_dwordx4 v206, s[22:23]
	v_mfma_f32_16x16x32_bf16 v[72:75], v[196:199], v[4:7], v[72:75]
	s_waitcnt lgkmcnt(0)
	s_add_u32 m0, s53, 0xc00
	v_mfma_f32_16x16x32_bf16 v[144:147], v[0:3], v[200:203], v[144:147]
	global_load_lds_dwordx4 v207, s[22:23]
	v_mfma_f32_16x16x32_bf16 v[76:79], v[200:203], v[4:7], v[76:79]
	s_waitcnt vmcnt(14)
	v_mov_b32_e32 v255, v88
	s_nop 7
	v_lshlrev_b32_e32 v242, 16, v186
	v_lshlrev_b32_e32 v243, 16, v188
	v_lshlrev_b32_e32 v244, 16, v185
	v_lshlrev_b32_e32 v245, 16, v89
	v_sub_f32_e32 v242, v242, v92
	v_sub_f32_e32 v243, v243, v93
	v_sub_f32_e32 v244, v244, v94
	v_sub_f32_e32 v245, v245, v95
	v_cvt_pk_bf16_f32 v242, v242, v243
	v_cvt_pk_bf16_f32 v243, v244, v245
	ds_write_b64 v247, v[242:243]
	v_lshlrev_b32_e32 v242, 16, v91
	v_lshlrev_b32_e32 v243, 16, v187
	v_lshlrev_b32_e32 v244, 16, v189
	v_lshlrev_b32_e32 v245, 16, v190
	v_sub_f32_e32 v242, v242, v144
	v_sub_f32_e32 v243, v243, v145
	v_sub_f32_e32 v244, v244, v146
	v_sub_f32_e32 v245, v245, v147
	v_cvt_pk_bf16_f32 v242, v242, v243
	v_cvt_pk_bf16_f32 v243, v244, v245
	ds_write_b64 v247, v[242:243] offset:2304
	global_load_ushort v186, v212, s[20:21] offset:0
	global_load_ushort v188, v212, s[20:21] offset:256
	global_load_ushort v185, v212, s[20:21] offset:512
	global_load_ushort v89, v212, s[20:21] offset:768
	global_load_ushort v91, v212, s[20:21] offset:32
	global_load_ushort v187, v212, s[20:21] offset:288
	global_load_ushort v189, v212, s[20:21] offset:544
	global_load_ushort v190, v212, s[20:21] offset:800
	global_load_dword v88, v113, s[46:47]
	s_waitcnt lgkmcnt(0)
	s_barrier
	s_waitcnt vmcnt(17)
	ds_read_b128 v[148:151], v248 offset:0
	ds_read_b128 v[192:195], v248 offset:2304
	ds_read_b128 v[196:199], v248 offset:64
	ds_read_b128 v[200:203], v248 offset:2368
	v_mul_f32_e32 v56, v56, v255
	v_mul_f32_e32 v57, v57, v255
	v_mul_f32_e32 v58, v58, v255
	v_mul_f32_e32 v59, v59, v255
	v_mul_f32_e32 v64, v64, v255
	v_mul_f32_e32 v65, v65, v255
	v_mul_f32_e32 v66, v66, v255
	v_mul_f32_e32 v67, v67, v255
	v_mul_f32_e32 v68, v68, v255
	v_mul_f32_e32 v69, v69, v255
	v_mul_f32_e32 v70, v70, v255
	v_mul_f32_e32 v71, v71, v255
	v_mul_f32_e32 v60, v60, v255
	v_mul_f32_e32 v61, v61, v255
	v_mul_f32_e32 v62, v62, v255
	v_mul_f32_e32 v63, v63, v255
	s_waitcnt lgkmcnt(3)
	v_mfma_f32_16x16x32_bf16 v[72:75], v[148:151], v[52:55], v[72:75]
	s_waitcnt lgkmcnt(2)
	v_mfma_f32_16x16x32_bf16 v[76:79], v[192:195], v[52:55], v[76:79]
	s_waitcnt lgkmcnt(1)
	v_mfma_f32_16x16x32_bf16 v[72:75], v[196:199], v[48:51], v[72:75]
	s_waitcnt lgkmcnt(0)
	v_mfma_f32_16x16x32_bf16 v[76:79], v[200:203], v[48:51], v[76:79]
	s_mov_b32 m0, s54
	v_mfma_f32_16x16x32_bf16 v[56:59], v[40:43], v[148:151], v[56:59]
	global_load_lds_dwordx4 v210, s[20:21]
	v_mfma_f32_16x16x32_bf16 v[64:67], v[40:43], v[192:195], v[64:67]
	v_mfma_f32_16x16x32_bf16 v[56:59], v[36:39], v[196:199], v[56:59]
	global_load_lds_dwordx4 v210, s[20:21] offset:1024
	v_mfma_f32_16x16x32_bf16 v[64:67], v[36:39], v[200:203], v[64:67]
	v_mfma_f32_16x16x32_bf16 v[68:71], v[8:11], v[148:151], v[68:71]
	global_load_lds_dwordx4 v210, s[20:21] offset:2048
	v_mfma_f32_16x16x32_bf16 v[60:63], v[8:11], v[192:195], v[60:63]
	v_mfma_f32_16x16x32_bf16 v[68:71], v[20:23], v[196:199], v[68:71]
	global_load_lds_dwordx4 v210, s[20:21] offset:3072
	v_mfma_f32_16x16x32_bf16 v[60:63], v[20:23], v[200:203], v[60:63]
	s_mov_b32 m0, s55
	s_nop 0
	global_load_lds_dwordx4 v211, s[20:21]
	s_nop 0
	global_load_lds_dwordx4 v211, s[20:21] offset:1024
	s_nop 3
	global_store_dwordx4 v[86:87], v[72:75], off
	global_store_dwordx4 v[86:87], v[76:79], off offset:64
	s_nop 7
	v_cvt_pk_bf16_f32 v242, v56, v57
	v_cvt_pk_bf16_f32 v243, v58, v59
	ds_write_b64 v249, v[242:243]
	v_cvt_pk_bf16_f32 v242, v64, v65
	v_cvt_pk_bf16_f32 v243, v66, v67
	ds_write_b64 v249, v[242:243] offset:4352
	v_cvt_pk_bf16_f32 v242, v68, v69
	v_cvt_pk_bf16_f32 v243, v70, v71
	ds_write_b64 v249, v[242:243] offset:32
	v_cvt_pk_bf16_f32 v242, v60, v61
	v_cvt_pk_bf16_f32 v243, v62, v63
	ds_write_b64 v249, v[242:243] offset:4384
	v_lshl_add_u64 v[86:87], v[86:87], 0, s[50:51]
	s_add_u32 s20, s20, 0x12000
	s_addc_u32 s21, s21, 0
	s_add_u32 s22, s22, 0x12000
	s_addc_u32 s23, s23, 0
	s_add_u32 s46, s46, 4
	s_addc_u32 s47, s47, 0
	s_waitcnt lgkmcnt(0)
	s_barrier
	s_waitcnt vmcnt(17)
	ds_read_b128 v[32:35], v213
	ds_read_b128 v[44:47], v213 offset:16384
	ds_read_b128 v[12:15], v214
	ds_read_b128 v[28:31], v214 offset:16384
	ds_read_b128 v[16:19], v215
	ds_read_b128 v[24:27], v215 offset:16384
	ds_read_b128 v[0:3], v216
	ds_read_b128 v[4:7], v216 offset:16384
	ds_read_b128 v[148:151], v246 offset:0
	ds_read_b128 v[192:195], v246 offset:4352
	ds_read_b128 v[196:199], v246 offset:64
	ds_read_b128 v[200:203], v246 offset:4416
	s_waitcnt lgkmcnt(4)
	s_waitcnt lgkmcnt(3)
	s_add_u32 m0, s52, 0x0
	v_mfma_f32_16x16x32_bf16 v[92:95], v[32:35], v[148:151], 0
	global_load_lds_dwordx4 v204, s[20:21]
	v_mfma_f32_16x16x32_bf16 v[72:75], v[148:151], v[44:47], 0
	s_waitcnt lgkmcnt(2)
	s_add_u32 m0, s52, 0x400
	v_mfma_f32_16x16x32_bf16 v[144:147], v[32:35], v[192:195], 0
	global_load_lds_dwordx4 v205, s[20:21]
	v_mfma_f32_16x16x32_bf16 v[76:79], v[192:195], v[44:47], 0
	ds_read_b128 v[148:151], v246 offset:128
	ds_read_b128 v[192:195], v246 offset:4480
	s_waitcnt lgkmcnt(3)
	s_add_u32 m0, s52, 0x800
	v_mfma_f32_16x16x32_bf16 v[92:95], v[12:15], v[196:199], v[92:95]
	global_load_lds_dwordx4 v206, s[20:21]
	v_mfma_f32_16x16x32_bf16 v[72:75], v[196:199], v[28:31], v[72:75]
	s_waitcnt lgkmcnt(2)
	s_add_u32 m0, s52, 0xc00
	v_mfma_f32_16x16x32_bf16 v[144:147], v[12:15], v[200:203], v[144:147]
	global_load_lds_dwordx4 v207, s[20:21]
	v_mfma_f32_16x16x32_bf16 v[76:79], v[200:203], v[28:31], v[76:79]
	ds_read_b128 v[196:199], v246 offset:192
	ds_read_b128 v[200:203], v246 offset:4544
	s_waitcnt lgkmcnt(3)
	s_add_u32 m0, s53, 0x0
	v_mfma_f32_16x16x32_bf16 v[92:95], v[16:19], v[148:151], v[92:95]
	global_load_lds_dwordx4 v204, s[22:23]
	v_mfma_f32_16x16x32_bf16 v[72:75], v[148:151], v[24:27], v[72:75]
	s_waitcnt lgkmcnt(2)
	s_add_u32 m0, s53, 0x400
	v_mfma_f32_16x16x32_bf16 v[144:147], v[16:19], v[192:195], v[144:147]
	global_load_lds_dwordx4 v205, s[22:23]
	v_mfma_f32_16x16x32_bf16 v[76:79], v[192:195], v[24:27], v[76:79]
	s_waitcnt lgkmcnt(1)
	s_add_u32 m0, s53, 0x800
	v_mfma_f32_16x16x32_bf16 v[92:95], v[0:3], v[196:199], v[92:95]
	global_load_lds_dwordx4 v206, s[22:23]
	v_mfma_f32_16x16x32_bf16 v[72:75], v[196:199], v[4:7], v[72:75]
	s_waitcnt lgkmcnt(0)
	s_add_u32 m0, s53, 0xc00
	v_mfma_f32_16x16x32_bf16 v[144:147], v[0:3], v[200:203], v[144:147]
	global_load_lds_dwordx4 v207, s[22:23]
	v_mfma_f32_16x16x32_bf16 v[76:79], v[200:203], v[4:7], v[76:79]
	s_waitcnt vmcnt(16)
	v_mov_b32_e32 v255, v88
	s_nop 7
	v_lshlrev_b32_e32 v242, 16, v186
	v_lshlrev_b32_e32 v243, 16, v188
	v_lshlrev_b32_e32 v244, 16, v185
	v_lshlrev_b32_e32 v245, 16, v89
	v_sub_f32_e32 v242, v242, v92
	v_sub_f32_e32 v243, v243, v93
	v_sub_f32_e32 v244, v244, v94
	v_sub_f32_e32 v245, v245, v95
	v_cvt_pk_bf16_f32 v242, v242, v243
	v_cvt_pk_bf16_f32 v243, v244, v245
	ds_write_b64 v247, v[242:243]
	v_lshlrev_b32_e32 v242, 16, v91
	v_lshlrev_b32_e32 v243, 16, v187
	v_lshlrev_b32_e32 v244, 16, v189
	v_lshlrev_b32_e32 v245, 16, v190
	v_sub_f32_e32 v242, v242, v144
	v_sub_f32_e32 v243, v243, v145
	v_sub_f32_e32 v244, v244, v146
	v_sub_f32_e32 v245, v245, v147
	v_cvt_pk_bf16_f32 v242, v242, v243
	v_cvt_pk_bf16_f32 v243, v244, v245
	ds_write_b64 v247, v[242:243] offset:2304
	global_load_ushort v186, v212, s[20:21] offset:0
	global_load_ushort v188, v212, s[20:21] offset:256
	global_load_ushort v185, v212, s[20:21] offset:512
	global_load_ushort v89, v212, s[20:21] offset:768
	global_load_ushort v91, v212, s[20:21] offset:32
	global_load_ushort v187, v212, s[20:21] offset:288
	global_load_ushort v189, v212, s[20:21] offset:544
	global_load_ushort v190, v212, s[20:21] offset:800
	global_load_dword v88, v113, s[46:47]
	s_waitcnt lgkmcnt(0)
	s_barrier
	s_waitcnt vmcnt(19)
	ds_read_b128 v[52:55], v221
	ds_read_b128 v[48:51], v222
	ds_read_b128 v[40:43], v217
	ds_read_b128 v[36:39], v220
	ds_read_b128 v[8:11], v217 offset:2048
	ds_read_b128 v[20:23], v220 offset:2048
	ds_read_b128 v[148:151], v248 offset:0
	ds_read_b128 v[192:195], v248 offset:2304
	ds_read_b128 v[196:199], v248 offset:64
	ds_read_b128 v[200:203], v248 offset:2368
	v_mul_f32_e32 v56, v56, v255
	v_mul_f32_e32 v57, v57, v255
	v_mul_f32_e32 v58, v58, v255
	v_mul_f32_e32 v59, v59, v255
	v_mul_f32_e32 v64, v64, v255
	v_mul_f32_e32 v65, v65, v255
	v_mul_f32_e32 v66, v66, v255
	v_mul_f32_e32 v67, v67, v255
	v_mul_f32_e32 v68, v68, v255
	v_mul_f32_e32 v69, v69, v255
	v_mul_f32_e32 v70, v70, v255
	v_mul_f32_e32 v71, v71, v255
	v_mul_f32_e32 v60, v60, v255
	v_mul_f32_e32 v61, v61, v255
	v_mul_f32_e32 v62, v62, v255
	v_mul_f32_e32 v63, v63, v255
	s_waitcnt lgkmcnt(4)
	s_waitcnt lgkmcnt(3)
	v_mfma_f32_16x16x32_bf16 v[72:75], v[148:151], v[52:55], v[72:75]
	s_waitcnt lgkmcnt(2)
	v_mfma_f32_16x16x32_bf16 v[76:79], v[192:195], v[52:55], v[76:79]
	s_waitcnt lgkmcnt(1)
	v_mfma_f32_16x16x32_bf16 v[72:75], v[196:199], v[48:51], v[72:75]
	s_waitcnt lgkmcnt(0)
	v_mfma_f32_16x16x32_bf16 v[76:79], v[200:203], v[48:51], v[76:79]
	s_mov_b32 m0, s54
	v_mfma_f32_16x16x32_bf16 v[56:59], v[40:43], v[148:151], v[56:59]
	global_load_lds_dwordx4 v210, s[20:21]
	v_mfma_f32_16x16x32_bf16 v[64:67], v[40:43], v[192:195], v[64:67]
	v_mfma_f32_16x16x32_bf16 v[56:59], v[36:39], v[196:199], v[56:59]
	global_load_lds_dwordx4 v210, s[20:21] offset:1024
	v_mfma_f32_16x16x32_bf16 v[64:67], v[36:39], v[200:203], v[64:67]
	v_mfma_f32_16x16x32_bf16 v[68:71], v[8:11], v[148:151], v[68:71]
	global_load_lds_dwordx4 v210, s[20:21] offset:2048
	v_mfma_f32_16x16x32_bf16 v[60:63], v[8:11], v[192:195], v[60:63]
	v_mfma_f32_16x16x32_bf16 v[68:71], v[20:23], v[196:199], v[68:71]
	global_load_lds_dwordx4 v210, s[20:21] offset:3072
	v_mfma_f32_16x16x32_bf16 v[60:63], v[20:23], v[200:203], v[60:63]
	s_mov_b32 m0, s55
	s_nop 0
	global_load_lds_dwordx4 v211, s[20:21]
	s_nop 0
	global_load_lds_dwordx4 v211, s[20:21] offset:1024
	s_nop 3
	global_store_dwordx4 v[86:87], v[72:75], off
	global_store_dwordx4 v[86:87], v[76:79], off offset:64
	s_nop 7
	v_cvt_pk_bf16_f32 v242, v56, v57
	v_cvt_pk_bf16_f32 v243, v58, v59
	ds_write_b64 v249, v[242:243]
	v_cvt_pk_bf16_f32 v242, v64, v65
	v_cvt_pk_bf16_f32 v243, v66, v67
	ds_write_b64 v249, v[242:243] offset:4352
	v_cvt_pk_bf16_f32 v242, v68, v69
	v_cvt_pk_bf16_f32 v243, v70, v71
	ds_write_b64 v249, v[242:243] offset:32
	v_cvt_pk_bf16_f32 v242, v60, v61
	v_cvt_pk_bf16_f32 v243, v62, v63
	ds_write_b64 v249, v[242:243] offset:4384
	v_lshl_add_u64 v[86:87], v[86:87], 0, s[50:51]
	s_add_u32 s20, s20, 0x12000
	s_addc_u32 s21, s21, 0
	s_add_u32 s22, s22, 0x12000
	s_addc_u32 s23, s23, 0
	s_add_u32 s46, s46, 4
	s_addc_u32 s47, s47, 0
	s_waitcnt lgkmcnt(0)
	s_barrier
	s_mov_b32 s1, 29
.Lseq_loop:
	s_waitcnt vmcnt(17)
	ds_read_b128 v[32:35], v213
	ds_read_b128 v[44:47], v213 offset:16384
	ds_read_b128 v[12:15], v214
	ds_read_b128 v[28:31], v214 offset:16384
	ds_read_b128 v[16:19], v215
	ds_read_b128 v[24:27], v215 offset:16384
	ds_read_b128 v[0:3], v216
	ds_read_b128 v[4:7], v216 offset:16384
	ds_read_b128 v[148:151], v246 offset:0
	ds_read_b128 v[192:195], v246 offset:4352
	ds_read_b128 v[196:199], v246 offset:64
	ds_read_b128 v[200:203], v246 offset:4416
	s_waitcnt lgkmcnt(4)
	s_waitcnt lgkmcnt(3)
	s_add_u32 m0, s52, 0x0
	v_mfma_f32_16x16x32_bf16 v[92:95], v[32:35], v[148:151], 0
	global_load_lds_dwordx4 v204, s[20:21]
	v_mfma_f32_16x16x32_bf16 v[72:75], v[148:151], v[44:47], 0
	s_waitcnt lgkmcnt(2)
	s_add_u32 m0, s52, 0x400
	v_mfma_f32_16x16x32_bf16 v[144:147], v[32:35], v[192:195], 0
	global_load_lds_dwordx4 v205, s[20:21]
	v_mfma_f32_16x16x32_bf16 v[76:79], v[192:195], v[44:47], 0
	ds_read_b128 v[148:151], v246 offset:128
	ds_read_b128 v[192:195], v246 offset:4480
	s_waitcnt lgkmcnt(3)
	s_add_u32 m0, s52, 0x800
	v_mfma_f32_16x16x32_bf16 v[92:95], v[12:15], v[196:199], v[92:95]
	global_load_lds_dwordx4 v206, s[20:21]
	v_mfma_f32_16x16x32_bf16 v[72:75], v[196:199], v[28:31], v[72:75]
	s_waitcnt lgkmcnt(2)
	s_add_u32 m0, s52, 0xc00
	v_mfma_f32_16x16x32_bf16 v[144:147], v[12:15], v[200:203], v[144:147]
	global_load_lds_dwordx4 v207, s[20:21]
	v_mfma_f32_16x16x32_bf16 v[76:79], v[200:203], v[28:31], v[76:79]
	ds_read_b128 v[196:199], v246 offset:192
	ds_read_b128 v[200:203], v246 offset:4544
	s_waitcnt lgkmcnt(3)
	s_add_u32 m0, s53, 0x0
	v_mfma_f32_16x16x32_bf16 v[92:95], v[16:19], v[148:151], v[92:95]
	global_load_lds_dwordx4 v204, s[22:23]
	v_mfma_f32_16x16x32_bf16 v[72:75], v[148:151], v[24:27], v[72:75]
	s_waitcnt lgkmcnt(2)
	s_add_u32 m0, s53, 0x400
	v_mfma_f32_16x16x32_bf16 v[144:147], v[16:19], v[192:195], v[144:147]
	global_load_lds_dwordx4 v205, s[22:23]
	v_mfma_f32_16x16x32_bf16 v[76:79], v[192:195], v[24:27], v[76:79]
	s_waitcnt lgkmcnt(1)
	s_add_u32 m0, s53, 0x800
	v_mfma_f32_16x16x32_bf16 v[92:95], v[0:3], v[196:199], v[92:95]
	global_load_lds_dwordx4 v206, s[22:23]
	v_mfma_f32_16x16x32_bf16 v[72:75], v[196:199], v[4:7], v[72:75]
	s_waitcnt lgkmcnt(0)
	s_add_u32 m0, s53, 0xc00
	v_mfma_f32_16x16x32_bf16 v[144:147], v[0:3], v[200:203], v[144:147]
	global_load_lds_dwordx4 v207, s[22:23]
	v_mfma_f32_16x16x32_bf16 v[76:79], v[200:203], v[4:7], v[76:79]
	s_waitcnt vmcnt(16)
	v_mov_b32_e32 v255, v88
	s_nop 7
	v_lshlrev_b32_e32 v242, 16, v186
	v_lshlrev_b32_e32 v243, 16, v188
	v_lshlrev_b32_e32 v244, 16, v185
	v_lshlrev_b32_e32 v245, 16, v89
	v_sub_f32_e32 v242, v242, v92
	v_sub_f32_e32 v243, v243, v93
	v_sub_f32_e32 v244, v244, v94
	v_sub_f32_e32 v245, v245, v95
	v_cvt_pk_bf16_f32 v242, v242, v243
	v_cvt_pk_bf16_f32 v243, v244, v245
	ds_write_b64 v247, v[242:243]
	v_lshlrev_b32_e32 v242, 16, v91
	v_lshlrev_b32_e32 v243, 16, v187
	v_lshlrev_b32_e32 v244, 16, v189
	v_lshlrev_b32_e32 v245, 16, v190
	v_sub_f32_e32 v242, v242, v144
	v_sub_f32_e32 v243, v243, v145
	v_sub_f32_e32 v244, v244, v146
	v_sub_f32_e32 v245, v245, v147
	v_cvt_pk_bf16_f32 v242, v242, v243
	v_cvt_pk_bf16_f32 v243, v244, v245
	ds_write_b64 v247, v[242:243] offset:2304
	global_load_ushort v186, v212, s[20:21] offset:0
	global_load_ushort v188, v212, s[20:21] offset:256
	global_load_ushort v185, v212, s[20:21] offset:512
	global_load_ushort v89, v212, s[20:21] offset:768
	global_load_ushort v91, v212, s[20:21] offset:32
	global_load_ushort v187, v212, s[20:21] offset:288
	global_load_ushort v189, v212, s[20:21] offset:544
	global_load_ushort v190, v212, s[20:21] offset:800
	global_load_dword v88, v113, s[46:47]
	s_waitcnt lgkmcnt(0)
	s_barrier
	s_waitcnt vmcnt(19)
	ds_read_b128 v[52:55], v221
	ds_read_b128 v[48:51], v222
	ds_read_b128 v[40:43], v217
	ds_read_b128 v[36:39], v220
	ds_read_b128 v[8:11], v217 offset:2048
	ds_read_b128 v[20:23], v220 offset:2048
	ds_read_b128 v[148:151], v248 offset:0
	ds_read_b128 v[192:195], v248 offset:2304
	ds_read_b128 v[196:199], v248 offset:64
	ds_read_b128 v[200:203], v248 offset:2368
	v_mul_f32_e32 v56, v56, v255
	v_mul_f32_e32 v57, v57, v255
	v_mul_f32_e32 v58, v58, v255
	v_mul_f32_e32 v59, v59, v255
	v_mul_f32_e32 v64, v64, v255
	v_mul_f32_e32 v65, v65, v255
	v_mul_f32_e32 v66, v66, v255
	v_mul_f32_e32 v67, v67, v255
	v_mul_f32_e32 v68, v68, v255
	v_mul_f32_e32 v69, v69, v255
	v_mul_f32_e32 v70, v70, v255
	v_mul_f32_e32 v71, v71, v255
	v_mul_f32_e32 v60, v60, v255
	v_mul_f32_e32 v61, v61, v255
	v_mul_f32_e32 v62, v62, v255
	v_mul_f32_e32 v63, v63, v255
	s_waitcnt lgkmcnt(4)
	s_waitcnt lgkmcnt(3)
	v_mfma_f32_16x16x32_bf16 v[72:75], v[148:151], v[52:55], v[72:75]
	s_waitcnt lgkmcnt(2)
	v_mfma_f32_16x16x32_bf16 v[76:79], v[192:195], v[52:55], v[76:79]
	s_waitcnt lgkmcnt(1)
	v_mfma_f32_16x16x32_bf16 v[72:75], v[196:199], v[48:51], v[72:75]
	s_waitcnt lgkmcnt(0)
	v_mfma_f32_16x16x32_bf16 v[76:79], v[200:203], v[48:51], v[76:79]
	s_mov_b32 m0, s54
	v_mfma_f32_16x16x32_bf16 v[56:59], v[40:43], v[148:151], v[56:59]
	global_load_lds_dwordx4 v210, s[20:21]
	v_mfma_f32_16x16x32_bf16 v[64:67], v[40:43], v[192:195], v[64:67]
	v_mfma_f32_16x16x32_bf16 v[56:59], v[36:39], v[196:199], v[56:59]
	global_load_lds_dwordx4 v210, s[20:21] offset:1024
	v_mfma_f32_16x16x32_bf16 v[64:67], v[36:39], v[200:203], v[64:67]
	v_mfma_f32_16x16x32_bf16 v[68:71], v[8:11], v[148:151], v[68:71]
	global_load_lds_dwordx4 v210, s[20:21] offset:2048
	v_mfma_f32_16x16x32_bf16 v[60:63], v[8:11], v[192:195], v[60:63]
	v_mfma_f32_16x16x32_bf16 v[68:71], v[20:23], v[196:199], v[68:71]
	global_load_lds_dwordx4 v210, s[20:21] offset:3072
	v_mfma_f32_16x16x32_bf16 v[60:63], v[20:23], v[200:203], v[60:63]
	s_mov_b32 m0, s55
	s_nop 0
	global_load_lds_dwordx4 v211, s[20:21]
	s_nop 0
	global_load_lds_dwordx4 v211, s[20:21] offset:1024
	s_nop 3
	global_store_dwordx4 v[86:87], v[72:75], off
	global_store_dwordx4 v[86:87], v[76:79], off offset:64
	s_nop 7
	v_cvt_pk_bf16_f32 v242, v56, v57
	v_cvt_pk_bf16_f32 v243, v58, v59
	ds_write_b64 v249, v[242:243]
	v_cvt_pk_bf16_f32 v242, v64, v65
	v_cvt_pk_bf16_f32 v243, v66, v67
	ds_write_b64 v249, v[242:243] offset:4352
	v_cvt_pk_bf16_f32 v242, v68, v69
	v_cvt_pk_bf16_f32 v243, v70, v71
	ds_write_b64 v249, v[242:243] offset:32
	v_cvt_pk_bf16_f32 v242, v60, v61
	v_cvt_pk_bf16_f32 v243, v62, v63
	ds_write_b64 v249, v[242:243] offset:4384
	v_lshl_add_u64 v[86:87], v[86:87], 0, s[50:51]
	s_add_u32 s20, s20, 0x12000
	s_addc_u32 s21, s21, 0
	s_add_u32 s22, s22, 0x12000
	s_addc_u32 s23, s23, 0
	s_add_u32 s46, s46, 4
	s_addc_u32 s47, s47, 0
	s_waitcnt lgkmcnt(0)
	s_barrier
	s_sub_u32 s1, s1, 1
	s_cmp_lg_u32 s1, 0
	s_cbranch_scc1 .Lseq_loop
	s_waitcnt vmcnt(17)
	ds_read_b128 v[32:35], v213
	ds_read_b128 v[44:47], v213 offset:16384
	ds_read_b128 v[12:15], v214
	ds_read_b128 v[28:31], v214 offset:16384
	ds_read_b128 v[16:19], v215
	ds_read_b128 v[24:27], v215 offset:16384
	ds_read_b128 v[0:3], v216
	ds_read_b128 v[4:7], v216 offset:16384
	ds_read_b128 v[148:151], v246 offset:0
	ds_read_b128 v[192:195], v246 offset:4352
	ds_read_b128 v[196:199], v246 offset:64
	ds_read_b128 v[200:203], v246 offset:4416
	s_waitcnt lgkmcnt(4)
	s_waitcnt lgkmcnt(3)
	v_mfma_f32_16x16x32_bf16 v[92:95], v[32:35], v[148:151], 0
	v_mfma_f32_16x16x32_bf16 v[72:75], v[148:151], v[44:47], 0
	s_waitcnt lgkmcnt(2)
	v_mfma_f32_16x16x32_bf16 v[144:147], v[32:35], v[192:195], 0
	v_mfma_f32_16x16x32_bf16 v[76:79], v[192:195], v[44:47], 0
	ds_read_b128 v[148:151], v246 offset:128
	ds_read_b128 v[192:195], v246 offset:4480
	s_waitcnt lgkmcnt(3)
	v_mfma_f32_16x16x32_bf16 v[92:95], v[12:15], v[196:199], v[92:95]
	v_mfma_f32_16x16x32_bf16 v[72:75], v[196:199], v[28:31], v[72:75]
	s_waitcnt lgkmcnt(2)
	v_mfma_f32_16x16x32_bf16 v[144:147], v[12:15], v[200:203], v[144:147]
	v_mfma_f32_16x16x32_bf16 v[76:79], v[200:203], v[28:31], v[76:79]
	ds_read_b128 v[196:199], v246 offset:192
	ds_read_b128 v[200:203], v246 offset:4544
	s_waitcnt lgkmcnt(3)
	v_mfma_f32_16x16x32_bf16 v[92:95], v[16:19], v[148:151], v[92:95]
	v_mfma_f32_16x16x32_bf16 v[72:75], v[148:151], v[24:27], v[72:75]
	s_waitcnt lgkmcnt(2)
	v_mfma_f32_16x16x32_bf16 v[144:147], v[16:19], v[192:195], v[144:147]
	v_mfma_f32_16x16x32_bf16 v[76:79], v[192:195], v[24:27], v[76:79]
	s_waitcnt lgkmcnt(1)
	v_mfma_f32_16x16x32_bf16 v[92:95], v[0:3], v[196:199], v[92:95]
	v_mfma_f32_16x16x32_bf16 v[72:75], v[196:199], v[4:7], v[72:75]
	s_waitcnt lgkmcnt(0)
	v_mfma_f32_16x16x32_bf16 v[144:147], v[0:3], v[200:203], v[144:147]
	v_mfma_f32_16x16x32_bf16 v[76:79], v[200:203], v[4:7], v[76:79]
	s_waitcnt vmcnt(8)
	v_mov_b32_e32 v255, v88
	s_nop 7
	v_lshlrev_b32_e32 v242, 16, v186
	v_lshlrev_b32_e32 v243, 16, v188
	v_lshlrev_b32_e32 v244, 16, v185
	v_lshlrev_b32_e32 v245, 16, v89
	v_sub_f32_e32 v242, v242, v92
	v_sub_f32_e32 v243, v243, v93
	v_sub_f32_e32 v244, v244, v94
	v_sub_f32_e32 v245, v245, v95
	v_cvt_pk_bf16_f32 v242, v242, v243
	v_cvt_pk_bf16_f32 v243, v244, v245
	ds_write_b64 v247, v[242:243]
	v_lshlrev_b32_e32 v242, 16, v91
	v_lshlrev_b32_e32 v243, 16, v187
	v_lshlrev_b32_e32 v244, 16, v189
	v_lshlrev_b32_e32 v245, 16, v190
	v_sub_f32_e32 v242, v242, v144
	v_sub_f32_e32 v243, v243, v145
	v_sub_f32_e32 v244, v244, v146
	v_sub_f32_e32 v245, v245, v147
	v_cvt_pk_bf16_f32 v242, v242, v243
	v_cvt_pk_bf16_f32 v243, v244, v245
	ds_write_b64 v247, v[242:243] offset:2304
	s_waitcnt lgkmcnt(0)
	s_barrier
	s_waitcnt vmcnt(2)
	ds_read_b128 v[52:55], v221
	ds_read_b128 v[48:51], v222
	ds_read_b128 v[40:43], v217
	ds_read_b128 v[36:39], v220
	ds_read_b128 v[8:11], v217 offset:2048
	ds_read_b128 v[20:23], v220 offset:2048
	ds_read_b128 v[148:151], v248 offset:0
	ds_read_b128 v[192:195], v248 offset:2304
	ds_read_b128 v[196:199], v248 offset:64
	ds_read_b128 v[200:203], v248 offset:2368
	v_mul_f32_e32 v56, v56, v255
	v_mul_f32_e32 v57, v57, v255
	v_mul_f32_e32 v58, v58, v255
	v_mul_f32_e32 v59, v59, v255
	v_mul_f32_e32 v64, v64, v255
	v_mul_f32_e32 v65, v65, v255
	v_mul_f32_e32 v66, v66, v255
	v_mul_f32_e32 v67, v67, v255
	v_mul_f32_e32 v68, v68, v255
	v_mul_f32_e32 v69, v69, v255
	v_mul_f32_e32 v70, v70, v255
	v_mul_f32_e32 v71, v71, v255
	v_mul_f32_e32 v60, v60, v255
	v_mul_f32_e32 v61, v61, v255
	v_mul_f32_e32 v62, v62, v255
	v_mul_f32_e32 v63, v63, v255
	s_waitcnt lgkmcnt(4)
	s_waitcnt lgkmcnt(3)
	v_mfma_f32_16x16x32_bf16 v[72:75], v[148:151], v[52:55], v[72:75]
	s_waitcnt lgkmcnt(2)
	v_mfma_f32_16x16x32_bf16 v[76:79], v[192:195], v[52:55], v[76:79]
	s_waitcnt lgkmcnt(1)
	v_mfma_f32_16x16x32_bf16 v[72:75], v[196:199], v[48:51], v[72:75]
	s_waitcnt lgkmcnt(0)
	v_mfma_f32_16x16x32_bf16 v[76:79], v[200:203], v[48:51], v[76:79]
	v_mfma_f32_16x16x32_bf16 v[56:59], v[40:43], v[148:151], v[56:59]
	v_mfma_f32_16x16x32_bf16 v[64:67], v[40:43], v[192:195], v[64:67]
	v_mfma_f32_16x16x32_bf16 v[56:59], v[36:39], v[196:199], v[56:59]
	v_mfma_f32_16x16x32_bf16 v[64:67], v[36:39], v[200:203], v[64:67]
	v_mfma_f32_16x16x32_bf16 v[68:71], v[8:11], v[148:151], v[68:71]
	v_mfma_f32_16x16x32_bf16 v[60:63], v[8:11], v[192:195], v[60:63]
	v_mfma_f32_16x16x32_bf16 v[68:71], v[20:23], v[196:199], v[68:71]
	v_mfma_f32_16x16x32_bf16 v[60:63], v[20:23], v[200:203], v[60:63]
	s_nop 3
	global_store_dwordx4 v[86:87], v[72:75], off
	global_store_dwordx4 v[86:87], v[76:79], off offset:64
	s_nop 7
	v_cvt_pk_bf16_f32 v242, v56, v57
	v_cvt_pk_bf16_f32 v243, v58, v59
	ds_write_b64 v249, v[242:243]
	v_cvt_pk_bf16_f32 v242, v64, v65
	v_cvt_pk_bf16_f32 v243, v66, v67
	ds_write_b64 v249, v[242:243] offset:4352
	v_cvt_pk_bf16_f32 v242, v68, v69
	v_cvt_pk_bf16_f32 v243, v70, v71
	ds_write_b64 v249, v[242:243] offset:32
	v_cvt_pk_bf16_f32 v242, v60, v61
	v_cvt_pk_bf16_f32 v243, v62, v63
	ds_write_b64 v249, v[242:243] offset:4384
	v_lshl_add_u64 v[86:87], v[86:87], 0, s[50:51]
	s_add_u32 s20, s20, 0x12000
	s_addc_u32 s21, s21, 0
	s_add_u32 s22, s22, 0x12000
	s_addc_u32 s23, s23, 0
	s_add_u32 s46, s46, 4
	s_addc_u32 s47, s47, 0
	s_waitcnt lgkmcnt(0)
	s_barrier
	s_branch .LBB0_520

	.amdhsa_kernel _Z14fwd_megakernel6Params
		.amdhsa_group_segment_fixed_size 76800
		.amdhsa_private_segment_fixed_size 0
		.amdhsa_kernarg_size 696
		.amdhsa_user_sgpr_count 2
		.amdhsa_user_sgpr_dispatch_ptr 0
		.amdhsa_user_sgpr_queue_ptr 0
		.amdhsa_user_sgpr_kernarg_segment_ptr 1
		.amdhsa_user_sgpr_dispatch_id 0
		.amdhsa_user_sgpr_kernarg_preload_length 0
		.amdhsa_user_sgpr_kernarg_preload_offset 0
		.amdhsa_user_sgpr_private_segment_size 0
		.amdhsa_uses_dynamic_stack 0
		.amdhsa_enable_private_segment 0
		.amdhsa_system_sgpr_workgroup_id_x 1
		.amdhsa_system_sgpr_workgroup_id_y 0
		.amdhsa_system_sgpr_workgroup_id_z 0
		.amdhsa_system_sgpr_workgroup_info 0
		.amdhsa_system_vgpr_workitem_id 2
		.amdhsa_next_free_vgpr 256
		.amdhsa_next_free_sgpr 102
		.amdhsa_accum_offset 256
		.amdhsa_reserve_vcc 1
		.amdhsa_float_round_mode_32 0
		.amdhsa_float_round_mode_16_64 0
		.amdhsa_float_denorm_mode_32 3
		.amdhsa_float_denorm_mode_16_64 3
		.amdhsa_dx10_clamp 1
		.amdhsa_ieee_mode 1
		.amdhsa_fp16_overflow 0
		.amdhsa_tg_split 0
		.amdhsa_exception_fp_ieee_invalid_op 0
		.amdhsa_exception_fp_denorm_src 0
		.amdhsa_exception_fp_ieee_div_zero 0
		.amdhsa_exception_fp_ieee_overflow 0
		.amdhsa_exception_fp_ieee_underflow 0
		.amdhsa_exception_fp_ieee_inexact 0
		.amdhsa_exception_int_div_zero 0
	.end_amdhsa_kernel

amdhsa.kernels:
  - .agpr_count:     0
    .args:
      - .offset:         0
        .size:           440
        .value_kind:     by_value
      - .offset:         440
        .size:           4
        .value_kind:     hidden_block_count_x
      - .offset:         444
        .size:           4
        .value_kind:     hidden_block_count_y
      - .offset:         448
        .size:           4
        .value_kind:     hidden_block_count_z
      - .offset:         452
        .size:           2
        .value_kind:     hidden_group_size_x
      - .offset:         454
        .size:           2
        .value_kind:     hidden_group_size_y
      - .offset:         456
        .size:           2
        .value_kind:     hidden_group_size_z
      - .offset:         458
        .size:           2
        .value_kind:     hidden_remainder_x
      - .offset:         460
        .size:           2
        .value_kind:     hidden_remainder_y
      - .offset:         462
        .size:           2
        .value_kind:     hidden_remainder_z
      - .offset:         480
        .size:           8
        .value_kind:     hidden_global_offset_x
      - .offset:         488
        .size:           8
        .value_kind:     hidden_global_offset_y
      - .offset:         496
        .size:           8
        .value_kind:     hidden_global_offset_z
      - .offset:         504
        .size:           2
        .value_kind:     hidden_grid_dims
      - .offset:         528
        .size:           8
        .value_kind:     hidden_multigrid_sync_arg
    .group_segment_fixed_size: 76800
    .kernarg_segment_align: 8
    .kernarg_segment_size: 696
    .language:       OpenCL C
    .language_version:
      - 2
      - 0
    .max_flat_workgroup_size: 256
    .name:           _Z14fwd_megakernel6Params
    .private_segment_fixed_size: 0
    .sgpr_count:     108
    .sgpr_spill_count: 176
    .symbol:         _Z14fwd_megakernel6Params.kd
    .uniform_work_group_size: 1
    .uses_dynamic_stack: false
    .vgpr_count:     256
    .vgpr_spill_count: 0
    .wavefront_size: 64
